# c1 bias loop: batch 64 loads per trip instead of one load per wait
# speedup vs baseline: 1.0259x; 1.0259x over previous
; __global__ void __launch_bounds__(512) mega(Params p) {
;     ...
;     if (bid < 8) {
;       const int l = bid >> 1, kv = bid & 1;
;       const float* pos = p.in[kv ? 7 : 4] + (size_t)l * 2048;
;       const float* w1 = p.in[kv ? 8 : 5] + (size_t)l * 2048 * 128;
;       const int n = tid & 127, part = tid >> 7;
;       float a = 0.f;
;       for (int k = part * 512; k < part * 512 + 512; ++k) a += pos[k] * w1[(size_t)k * 128 + n];
.LBB0_216:
	s_or_b64 exec, exec, s[0:1]
	s_load_dwordx4 s[4:7], s[78:79], 0xa0
	s_load_dwordx16 s[8:23], s[78:79], 0x0
	s_waitcnt lgkmcnt(0)
	s_add_u32 s0, s6, 0x1f400000
	s_addc_u32 s1, s7, 0
	v_writelane_b32 v253, s0, 10
	s_cmp_lt_i32 s76, 8
	s_nop 0
	v_writelane_b32 v253, s1, 11
	s_cbranch_scc0 .LBB0_222
	s_load_dwordx16 s[36:51], s[78:79], 0x40
	s_ashr_i32 s2, s76, 1
	s_ashr_i32 s3, s2, 31
	s_and_b32 s6, s76, 1
	s_lshl_b64 s[4:5], s[2:3], 13
	s_cmp_eq_u32 s6, 0
	s_waitcnt lgkmcnt(0)
	s_mov_b64 s[12:13], s[36:37]
	s_cselect_b32 s8, s17, s23
	s_cselect_b32 s9, s16, s22
	s_cselect_b32 s7, s19, s13
	s_cselect_b32 s6, s18, s12
	s_lshl_b64 s[2:3], s[2:3], 20
	v_lshlrev_b32_e32 v3, 2, v2
	v_and_b32_e32 v8, 0xfffffe00, v3
	s_add_u32 s4, s9, s4
	v_ashrrev_i32_e32 v9, 31, v8
	s_addc_u32 s5, s8, s5
	v_add_u32_e32 v5, -1, v8
	v_lshl_add_u64 v[6:7], v[8:9], 2, s[4:5]
	v_lshlrev_b64 v[8:9], 9, v[8:9]
	v_and_b32_e32 v10, 0x7f, v2
	v_lshl_add_u64 v[8:9], s[2:3], 0, v[8:9]
	v_lshl_or_b32 v8, v10, 2, v8
	v_or_b32_e32 v3, 0x1ff, v3
	v_lshl_add_u64 v[8:9], s[6:7], 0, v[8:9]
	v_mov_b32_e32 v10, 0
	s_mov_b32 s2, 0
	s_mov_b64 s[4:5], 0x1000
	s_mov_b64 s[6:7], 0x100
.Lc1_batch:
	global_load_dword v110, v[6:7], off
	global_load_dword v111, v[6:7], off offset:4
	global_load_dword v112, v[6:7], off offset:8
	global_load_dword v113, v[6:7], off offset:12
	global_load_dword v114, v[6:7], off offset:16
	global_load_dword v115, v[6:7], off offset:20
	global_load_dword v116, v[6:7], off offset:24
	global_load_dword v117, v[6:7], off offset:28
	global_load_dword v118, v[6:7], off offset:32
	global_load_dword v119, v[6:7], off offset:36
	global_load_dword v120, v[6:7], off offset:40
	global_load_dword v121, v[6:7], off offset:44
	global_load_dword v122, v[6:7], off offset:48
	global_load_dword v123, v[6:7], off offset:52
	global_load_dword v124, v[6:7], off offset:56
	global_load_dword v125, v[6:7], off offset:60
	global_load_dword v126, v[6:7], off offset:64
	global_load_dword v127, v[6:7], off offset:68
	global_load_dword v128, v[6:7], off offset:72
	global_load_dword v129, v[6:7], off offset:76
	global_load_dword v130, v[6:7], off offset:80
	global_load_dword v131, v[6:7], off offset:84
	global_load_dword v132, v[6:7], off offset:88
	global_load_dword v133, v[6:7], off offset:92
	global_load_dword v134, v[6:7], off offset:96
	global_load_dword v135, v[6:7], off offset:100
	global_load_dword v136, v[6:7], off offset:104
	global_load_dword v137, v[6:7], off offset:108
	global_load_dword v138, v[6:7], off offset:112
	global_load_dword v139, v[6:7], off offset:116
	global_load_dword v140, v[6:7], off offset:120
	global_load_dword v141, v[6:7], off offset:124
	global_load_dword v142, v[6:7], off offset:128
	global_load_dword v143, v[6:7], off offset:132
	global_load_dword v144, v[6:7], off offset:136
	global_load_dword v145, v[6:7], off offset:140
	global_load_dword v146, v[6:7], off offset:144
	global_load_dword v147, v[6:7], off offset:148
	global_load_dword v148, v[6:7], off offset:152
	global_load_dword v149, v[6:7], off offset:156
	global_load_dword v150, v[6:7], off offset:160
	global_load_dword v151, v[6:7], off offset:164
	global_load_dword v152, v[6:7], off offset:168
	global_load_dword v153, v[6:7], off offset:172
	global_load_dword v154, v[6:7], off offset:176
	global_load_dword v155, v[6:7], off offset:180
	global_load_dword v156, v[6:7], off offset:184
	global_load_dword v157, v[6:7], off offset:188
	global_load_dword v158, v[6:7], off offset:192
	global_load_dword v159, v[6:7], off offset:196
	global_load_dword v160, v[6:7], off offset:200
	global_load_dword v161, v[6:7], off offset:204
	global_load_dword v162, v[6:7], off offset:208
	global_load_dword v163, v[6:7], off offset:212
	global_load_dword v164, v[6:7], off offset:216
	global_load_dword v165, v[6:7], off offset:220
	global_load_dword v166, v[6:7], off offset:224
	global_load_dword v167, v[6:7], off offset:228
	global_load_dword v168, v[6:7], off offset:232
	global_load_dword v169, v[6:7], off offset:236
	global_load_dword v170, v[6:7], off offset:240
	global_load_dword v171, v[6:7], off offset:244
	global_load_dword v172, v[6:7], off offset:248
	global_load_dword v173, v[6:7], off offset:252
	global_load_dword v174, v[8:9], off
	global_load_dword v175, v[8:9], off offset:512
	global_load_dword v176, v[8:9], off offset:1024
	global_load_dword v177, v[8:9], off offset:1536
	global_load_dword v178, v[8:9], off offset:2048
	global_load_dword v179, v[8:9], off offset:2560
	global_load_dword v180, v[8:9], off offset:3072
	global_load_dword v181, v[8:9], off offset:3584
	v_lshl_add_u64 v[8:9], v[8:9], 0, s[4:5]
	global_load_dword v182, v[8:9], off
	global_load_dword v183, v[8:9], off offset:512
	global_load_dword v184, v[8:9], off offset:1024
	global_load_dword v185, v[8:9], off offset:1536
	global_load_dword v186, v[8:9], off offset:2048
	global_load_dword v187, v[8:9], off offset:2560
	global_load_dword v188, v[8:9], off offset:3072
	global_load_dword v189, v[8:9], off offset:3584
	v_lshl_add_u64 v[8:9], v[8:9], 0, s[4:5]
	global_load_dword v190, v[8:9], off
	global_load_dword v191, v[8:9], off offset:512
	global_load_dword v192, v[8:9], off offset:1024
	global_load_dword v193, v[8:9], off offset:1536
	global_load_dword v194, v[8:9], off offset:2048
	global_load_dword v195, v[8:9], off offset:2560
	global_load_dword v196, v[8:9], off offset:3072
	global_load_dword v197, v[8:9], off offset:3584
	v_lshl_add_u64 v[8:9], v[8:9], 0, s[4:5]
	global_load_dword v198, v[8:9], off
	global_load_dword v199, v[8:9], off offset:512
	global_load_dword v200, v[8:9], off offset:1024
	global_load_dword v201, v[8:9], off offset:1536
; __global__ void __launch_bounds__(512) mega(Params p) {
;     ...
;       for (int k = part * 512; k < part * 512 + 512; ++k) a += pos[k] * w1[(size_t)k * 128 + n];
;       float* red = (float*)lds;
;       __syncthreads();
;       red[tid] = a;
;       __syncthreads();
;       if (tid < 128) cx.c1[(l * 2 + kv) * 128 + tid] = red[tid] + red[tid + 128] + red[tid + 256] + red[tid + 384];
	global_load_dword v202, v[8:9], off offset:2048
	global_load_dword v203, v[8:9], off offset:2560
	global_load_dword v204, v[8:9], off offset:3072
	global_load_dword v205, v[8:9], off offset:3584
	v_lshl_add_u64 v[8:9], v[8:9], 0, s[4:5]
	global_load_dword v206, v[8:9], off
	global_load_dword v207, v[8:9], off offset:512
	global_load_dword v208, v[8:9], off offset:1024
	global_load_dword v209, v[8:9], off offset:1536
	global_load_dword v210, v[8:9], off offset:2048
	global_load_dword v211, v[8:9], off offset:2560
	global_load_dword v212, v[8:9], off offset:3072
	global_load_dword v213, v[8:9], off offset:3584
	v_lshl_add_u64 v[8:9], v[8:9], 0, s[4:5]
	global_load_dword v214, v[8:9], off
	global_load_dword v215, v[8:9], off offset:512
	global_load_dword v216, v[8:9], off offset:1024
	global_load_dword v217, v[8:9], off offset:1536
	global_load_dword v218, v[8:9], off offset:2048
	global_load_dword v219, v[8:9], off offset:2560
	global_load_dword v220, v[8:9], off offset:3072
	global_load_dword v221, v[8:9], off offset:3584
	v_lshl_add_u64 v[8:9], v[8:9], 0, s[4:5]
	global_load_dword v222, v[8:9], off
	global_load_dword v223, v[8:9], off offset:512
	global_load_dword v224, v[8:9], off offset:1024
	global_load_dword v225, v[8:9], off offset:1536
	global_load_dword v226, v[8:9], off offset:2048
	global_load_dword v227, v[8:9], off offset:2560
	global_load_dword v228, v[8:9], off offset:3072
	global_load_dword v229, v[8:9], off offset:3584
	v_lshl_add_u64 v[8:9], v[8:9], 0, s[4:5]
	global_load_dword v230, v[8:9], off
	global_load_dword v231, v[8:9], off offset:512
	global_load_dword v232, v[8:9], off offset:1024
	global_load_dword v233, v[8:9], off offset:1536
	global_load_dword v234, v[8:9], off offset:2048
	global_load_dword v235, v[8:9], off offset:2560
	global_load_dword v236, v[8:9], off offset:3072
	global_load_dword v237, v[8:9], off offset:3584
	v_lshl_add_u64 v[8:9], v[8:9], 0, s[4:5]
	v_lshl_add_u64 v[6:7], v[6:7], 0, s[6:7]
	s_add_i32 s2, s2, 1
	s_waitcnt vmcnt(63)
	v_fmac_f32_e32 v10, v110, v174
	s_waitcnt vmcnt(62)
	v_fmac_f32_e32 v10, v111, v175
	s_waitcnt vmcnt(61)
	v_fmac_f32_e32 v10, v112, v176
	s_waitcnt vmcnt(60)
	v_fmac_f32_e32 v10, v113, v177
	s_waitcnt vmcnt(59)
	v_fmac_f32_e32 v10, v114, v178
	s_waitcnt vmcnt(58)
	v_fmac_f32_e32 v10, v115, v179
	s_waitcnt vmcnt(57)
	v_fmac_f32_e32 v10, v116, v180
	s_waitcnt vmcnt(56)
	v_fmac_f32_e32 v10, v117, v181
	s_waitcnt vmcnt(55)
	v_fmac_f32_e32 v10, v118, v182
	s_waitcnt vmcnt(54)
	v_fmac_f32_e32 v10, v119, v183
	s_waitcnt vmcnt(53)
	v_fmac_f32_e32 v10, v120, v184
	s_waitcnt vmcnt(52)
	v_fmac_f32_e32 v10, v121, v185
	s_waitcnt vmcnt(51)
	v_fmac_f32_e32 v10, v122, v186
	s_waitcnt vmcnt(50)
	v_fmac_f32_e32 v10, v123, v187
	s_waitcnt vmcnt(49)
	v_fmac_f32_e32 v10, v124, v188
	s_waitcnt vmcnt(48)
	v_fmac_f32_e32 v10, v125, v189
	s_waitcnt vmcnt(47)
	v_fmac_f32_e32 v10, v126, v190
	s_waitcnt vmcnt(46)
	v_fmac_f32_e32 v10, v127, v191
	s_waitcnt vmcnt(45)
	v_fmac_f32_e32 v10, v128, v192
	s_waitcnt vmcnt(44)
	v_fmac_f32_e32 v10, v129, v193
	s_waitcnt vmcnt(43)
	v_fmac_f32_e32 v10, v130, v194
	s_waitcnt vmcnt(42)
	v_fmac_f32_e32 v10, v131, v195
	s_waitcnt vmcnt(41)
	v_fmac_f32_e32 v10, v132, v196
	s_waitcnt vmcnt(40)
	v_fmac_f32_e32 v10, v133, v197
	s_waitcnt vmcnt(39)
	v_fmac_f32_e32 v10, v134, v198
	s_waitcnt vmcnt(38)
	v_fmac_f32_e32 v10, v135, v199
	s_waitcnt vmcnt(37)
	v_fmac_f32_e32 v10, v136, v200
	s_waitcnt vmcnt(36)
	v_fmac_f32_e32 v10, v137, v201
	s_waitcnt vmcnt(35)
	v_fmac_f32_e32 v10, v138, v202
	s_waitcnt vmcnt(34)
	v_fmac_f32_e32 v10, v139, v203
	s_waitcnt vmcnt(33)
	v_fmac_f32_e32 v10, v140, v204
	s_waitcnt vmcnt(32)
	v_fmac_f32_e32 v10, v141, v205
	s_waitcnt vmcnt(31)
	v_fmac_f32_e32 v10, v142, v206
	s_waitcnt vmcnt(30)
	v_fmac_f32_e32 v10, v143, v207
	s_waitcnt vmcnt(29)
	v_fmac_f32_e32 v10, v144, v208
	s_waitcnt vmcnt(28)
	v_fmac_f32_e32 v10, v145, v209
	s_waitcnt vmcnt(27)
	v_fmac_f32_e32 v10, v146, v210
	s_waitcnt vmcnt(26)
	v_fmac_f32_e32 v10, v147, v211
	s_waitcnt vmcnt(25)
	v_fmac_f32_e32 v10, v148, v212
	s_waitcnt vmcnt(24)
	v_fmac_f32_e32 v10, v149, v213
	s_waitcnt vmcnt(23)
	v_fmac_f32_e32 v10, v150, v214
	s_waitcnt vmcnt(22)
	v_fmac_f32_e32 v10, v151, v215
	s_waitcnt vmcnt(21)
	v_fmac_f32_e32 v10, v152, v216
	s_waitcnt vmcnt(20)
	v_fmac_f32_e32 v10, v153, v217
	s_waitcnt vmcnt(19)
	v_fmac_f32_e32 v10, v154, v218
	s_waitcnt vmcnt(18)
	v_fmac_f32_e32 v10, v155, v219
	s_waitcnt vmcnt(17)
	v_fmac_f32_e32 v10, v156, v220
	s_waitcnt vmcnt(16)
	v_fmac_f32_e32 v10, v157, v221
	s_waitcnt vmcnt(15)
	v_fmac_f32_e32 v10, v158, v222
	s_waitcnt vmcnt(14)
	v_fmac_f32_e32 v10, v159, v223
	s_waitcnt vmcnt(13)
	v_fmac_f32_e32 v10, v160, v224
	s_waitcnt vmcnt(12)
	v_fmac_f32_e32 v10, v161, v225
	s_waitcnt vmcnt(11)
	v_fmac_f32_e32 v10, v162, v226
	s_waitcnt vmcnt(10)
	v_fmac_f32_e32 v10, v163, v227
	s_waitcnt vmcnt(9)
	v_fmac_f32_e32 v10, v164, v228
	s_waitcnt vmcnt(8)
	v_fmac_f32_e32 v10, v165, v229
	s_waitcnt vmcnt(7)
	v_fmac_f32_e32 v10, v166, v230
	s_waitcnt vmcnt(6)
	v_fmac_f32_e32 v10, v167, v231
	s_waitcnt vmcnt(5)
	v_fmac_f32_e32 v10, v168, v232
	s_waitcnt vmcnt(4)
	v_fmac_f32_e32 v10, v169, v233
	s_waitcnt vmcnt(3)
	v_fmac_f32_e32 v10, v170, v234
	s_waitcnt vmcnt(2)
	v_fmac_f32_e32 v10, v171, v235
	s_waitcnt vmcnt(1)
	v_fmac_f32_e32 v10, v172, v236
	s_waitcnt vmcnt(0)
	v_fmac_f32_e32 v10, v173, v237
	s_cmp_lt_u32 s2, 8
	s_cbranch_scc1 .Lc1_batch
	s_movk_i32 s2, 0x80
	v_lshl_add_u32 v3, v2, 2, 0
	v_cmp_gt_i32_e32 vcc, s2, v2
	s_barrier
	ds_write_b32 v3, v10
	s_waitcnt lgkmcnt(0)
	s_barrier
	s_and_saveexec_b64 s[2:3], vcc
	s_cbranch_execz .LBB0_221
	ds_read2st64_b32 v[6:7], v3 offset1:2
	ds_read2st64_b32 v[2:3], v3 offset0:4 offset1:6
	s_mul_i32 s4, s76, 0xfffffe80
	v_add_u32_e32 v4, s4, v4
	v_readlane_b32 s0, v253, 10
	s_waitcnt lgkmcnt(1)
	v_add_f32_e32 v6, v6, v7
	v_ashrrev_i32_e32 v5, 31, v4
	s_waitcnt lgkmcnt(0)
	v_add_f32_e32 v2, v6, v2
	v_readlane_b32 s1, v253, 11
	v_add_f32_e32 v6, v2, v3
	s_nop 0
	v_lshl_add_u64 v[2:3], v[4:5], 2, s[0:1]
	global_store_dword v[2:3], v6, off
